# v15 + band-only workgroups arrive at but do not wait on the grid barrier before the scan+band phase (they depend only on in-proj output)
# speedup vs baseline: 1.0094x; 1.0094x over previous
; __device__ __forceinline__ unsigned xb_ld(unsigned* p)              { return __hip_atomic_load(p, __ATOMIC_RELAXED, __HIP_MEMORY_SCOPE_AGENT); }
; __device__ __forceinline__ unsigned xb_add(unsigned* p, unsigned v) { return __hip_atomic_fetch_add(p, v, __ATOMIC_RELAXED, __HIP_MEMORY_SCOPE_AGENT); }
; #define XB_SPIN(cond, bar) do { unsigned _sp = 0; while (cond) { __builtin_amdgcn_s_sleep(1); \
;     if ((++_sp & 255u) == 0u) { if (xb_ld(&(bar)[XB_TMO])) break; if (_sp > XB_SPIN_CAP) { atomicAdd(&(bar)[XB_TMO], 1u); break; } } } } while (0)
; __device__ __forceinline__ void xcd_barrier(const XcdBarrier& b) {
;     ...
;         const unsigned old = xb_add(&bar[XB_XSUB(b.x)], 1u);
;         const unsigned gen = old / nloc;
;         if (old + 1u == (gen + 1u) * nloc) {
;             __builtin_amdgcn_fence(__ATOMIC_RELEASE, "agent");
;             asm volatile("s_waitcnt vmcnt(0)" ::: "memory");
;             const unsigned og = xb_add(&bar[XB_TOP], 1u);
;             const unsigned tg = og / nx;
;             if (og + 1u == (tg + 1u) * nx) xb_add(&bar[XB_TOPGEN], 1u);
;             else XB_SPIN(xb_ld(&bar[XB_TOPGEN]) == tg, bar);
;             __builtin_amdgcn_fence(__ATOMIC_ACQUIRE, "agent");
;             xb_add(&bar[XB_XGEN(b.x)], 1u);
;             asm volatile("s_waitcnt vmcnt(0)" ::: "memory");
;         } else {
;             XB_SPIN(xb_ld(&bar[XB_XGEN(b.x)]) == gen, bar);
;             __builtin_amdgcn_fence(__ATOMIC_ACQUIRE, "agent");
;             asm volatile("s_waitcnt vmcnt(0)" ::: "memory");
;         }
.LBB0_40:
	s_or_b64 exec, exec, s[4:5]
	v_cvt_f32_u32_e32 v4, v2
	s_waitcnt vmcnt(0)
	v_readfirstlane_b32 s4, v3
	v_sub_u32_e32 v3, 0, v2
	v_rcp_iflag_f32_e32 v4, v4
	v_add_u32_e32 v5, s4, v1
	v_mul_f32_e32 v4, 0x4f7ffffe, v4
	v_cvt_u32_f32_e32 v4, v4
	v_mul_lo_u32 v1, v3, v4
	v_mul_hi_u32 v1, v4, v1
	v_add_u32_e32 v1, v4, v1
	v_mul_hi_u32 v1, v5, v1
	v_mul_lo_u32 v3, v1, v2
	v_sub_u32_e32 v3, v5, v3
	v_add_u32_e32 v4, 1, v1
	v_sub_u32_e32 v6, v3, v2
	v_cmp_ge_u32_e32 vcc, v3, v2
	s_nop 1
	v_cndmask_b32_e32 v1, v1, v4, vcc
	v_cndmask_b32_e32 v3, v3, v6, vcc
	v_add_u32_e32 v4, 1, v1
	v_cmp_ge_u32_e32 vcc, v3, v2
	v_add_u32_e32 v3, 1, v5
	s_nop 0
	v_cndmask_b32_e32 v1, v1, v4, vcc
	v_mul_lo_u32 v4, v2, v1
	v_add_u32_e32 v2, v4, v2
	v_cmp_ne_u32_e32 vcc, v3, v2
	s_and_saveexec_b64 s[4:5], vcc
	s_xor_b64 s[4:5], exec, s[4:5]
	s_cbranch_execz .LBB0_54
	s_cmp_eq_u32 s94, 3
	s_cbranch_scc1 .Lskipw_chk
	s_cmp_lg_u32 s94, 9
	s_cbranch_scc1 .Lskipw_no
.Lskipw_chk:
	v_readlane_b32 s6, v248, 59
	s_cmp_lt_u32 s6, 0x88
	s_cbranch_scc1 .Lskipw_no
	s_branch .LBB0_54
.Lskipw_no:
	v_readlane_b32 s6, v248, 8
	v_readlane_b32 s7, v248, 9
	s_waitcnt lgkmcnt(0)
	s_nop 3
	global_load_dword v0, v137, s[6:7] sc1
	s_waitcnt vmcnt(0)
	v_cmp_eq_u32_e32 vcc, v0, v1
	s_and_saveexec_b64 s[6:7], vcc
	s_cbranch_execz .LBB0_53
	s_mov_b32 s18, 1
	s_mov_b64 s[8:9], 0
	s_branch .LBB0_44
